# m2 + MLA loop: the two next-tile pointer advances moved from the loop tail into the idle slots after the last QK MFMA (MFMA-shadow fill)
# speedup vs baseline: 1.0027x; 1.0027x over previous
; template <int DK, int MODE, bool OUTF32> ...
;     ...
;     for (int t = t_lo; t < t_hi; ++t) {
;         const int cur = (t - t_lo) & 1;
;         if (t + 1 < t_hi) A_ISSUE(t + 1);
.LBB0_958:
	s_or_b64 exec, exec, s[50:51]
	s_xor_b32 s13, s13, 1
	s_mul_i32 s14, s13, 0x6400
	s_add_i32 s14, s14, 0
	v_add3_u32 v2, s14, v180, v183
	s_waitcnt vmcnt(4)
	ds_write_b128 v2, v[12:15]
	v_add3_u32 v2, s14, v181, v184
	s_lshl_b32 s13, s13, 13
	s_waitcnt vmcnt(3)
	ds_write_b128 v2, v[4:7]
	v_add3_u32 v2, s14, v182, v185
	s_sub_i32 s13, s14, s13
	s_waitcnt vmcnt(2)
	ds_write_b128 v2, v[8:11]
	v_add_u32_e32 v2, s13, v177
	s_mov_b32 s14, 0xc800
	s_add_i32 s12, s12, 1
	v_add3_u32 v2, v2, v160, s14
	s_waitcnt vmcnt(1)
	ds_write2_b64 v2, v[150:151], v[152:153] offset1:1
	v_add_u32_e32 v2, s13, v178
	v_cmp_eq_u32_e32 vcc, s12, v175
	v_add3_u32 v2, v2, v160, s14
	s_or_b64 s[42:43], vcc, s[42:43]
	s_waitcnt vmcnt(0)
	ds_write2_b64 v2, v[146:147], v[148:149] offset1:1
	s_and_b32 s13, s12, 1
	s_mul_i32 s14, s13, 0x6400
	v_add_u32_e32 v254, s14, v176
	s_waitcnt lgkmcnt(0)
	s_andn2_b64 exec, exec, s[42:43]
	s_cbranch_execz .Lmq_exit

; template <int DK, int MODE, bool OUTF32> ...
;     ...
;     for (int t = t_lo; t < t_hi; ++t) {
;         const int cur = (t - t_lo) & 1;
;         if (t + 1 < t_hi) A_ISSUE(t + 1);
;         bool act;
;         if (MODE == 0) act = (64 * t + 32 * kh) <= (qw0 + 31);
;         else if (MODE == 1) act = (t <= cw) && (t >= cw - 8);
;         else act = (t <= cw);
;         if (act) {
;             f32x16 p;
; #pragma unroll
;             for (int r = 0; r < 16; ++r) p[r] = 0.f;
;             const unsigned char* kb = a_lds + cur * KBUF + (32 * kh + c) * KP + hi * 16;
;             constexpr bool HOISTK = true;
;             bf16x8 kf[NKS];
;             if (HOISTK) {
; #pragma unroll
;                 for (int s = 0; s < NKS; ++s) kf[s] = *(const bf16x8*)(kb + s * 32);
;             }
;             const unsigned char* vb = a_lds + OFF_V + cur * VBUF + c * VP + (32 * kh + 4 * hi) * 2;
;             bf16x8 vf[8];
;     ...
;             constexpr bool HOISTV = (DK == 128) && (MODE == 2 || MODE == 1);
;             if (HOISTV) A_VREADS(0, 3);
;             if (HOISTK) __builtin_amdgcn_sched_barrier(0);
; #pragma unroll
;             for (int s = 0; s < NKS; ++s) p = __builtin_amdgcn_mfma_f32_32x32x16_bf16(HOISTK ? kf[s] : *(const bf16x8*)(kb + s * 32), qf[s], p, 0, 0, 0);
;             if (HOISTV) { A_VREADS(3, 4); __builtin_amdgcn_sched_barrier(0); }
;             if (MODE == 0) {
;                 const float* ckp = (const float*)(a_lds + OFF_CK + cur * 256) + 32 * kh + 4 * hi;
; #pragma unroll
;                 for (int g = 0; g < 4; ++g) {
;                     const float4 ck = *(const float4*)(ckp + 8 * g);
;                     p[4 * g + 0] = fmaf(p[4 * g + 0], sc2, cq - ck.x); p[4 * g + 1] = fmaf(p[4 * g + 1], sc2, cq - ck.y);
;                     p[4 * g + 2] = fmaf(p[4 * g + 2], sc2, cq - ck.z); p[4 * g + 3] = fmaf(p[4 * g + 3], sc2, cq - ck.w);
;                 }
;                 if (64 * t + 32 * kh + 31 > qw0) {
;                     const int kbase = 64 * t + 32 * kh + 4 * hi;
; #pragma unroll
;                     for (int r = 0; r < 16; ++r) if (kbase + (r & 3) + 8 * (r >> 2) > qrow) p[r] = NEGINF;
;                 }
;             } else if (MODE == 1) {
;                 const float* rb = (const float*)(a_lds + OFF_RB);
;                 if (t <= cw - 3) {
;                     const float bb = rb[256];
; #pragma unroll
.LBB0_959:
	v_cmp_le_i32_e32 vcc, s12, v179
	s_and_saveexec_b64 s[50:51], vcc
	s_cbranch_execz .Lmla_inact
	ds_read_b128 v[82:85], v254
	ds_read_b128 v[186:189], v254 offset:32
	ds_read_b128 v[190:193], v254 offset:64
	ds_read_b128 v[194:197], v254 offset:96
	ds_read_b128 v[208:211], v254 offset:128
	ds_read_b128 v[212:215], v254 offset:160
	ds_read_b128 v[216:219], v254 offset:192
	ds_read_b128 v[220:223], v254 offset:224
	ds_read_b128 v[224:227], v254 offset:256
	ds_read_b128 v[228:231], v254 offset:288
	ds_read_b128 v[232:235], v254 offset:320
	ds_read_b128 v[236:239], v254 offset:352
	v_add_co_u32_e32 v246, vcc, 0xfff80000, v162
	v_lshl_add_u64 v[240:241], v[158:159], 0, v[164:165]
	v_lshl_add_u64 v[242:243], v[158:159], 0, v[168:169]
	v_lshl_add_u64 v[244:245], v[158:159], 0, v[166:167]
	v_addc_co_u32_e32 v247, vcc, -1, v163, vcc
	global_load_dwordx4 v[12:15], v[240:241], off
	global_load_dwordx4 v[4:7], v[242:243], off
	global_load_dwordx4 v[8:11], v[244:245], off
	global_load_dwordx4 v[150:153], v[246:247], off
	global_load_dwordx4 v[146:149], v[162:163], off
	s_waitcnt lgkmcnt(11)
	v_mfma_f32_32x32x16_bf16 v[82:97], v[82:85], v[142:145], 0
	s_mov_b32 s14, 0x41000000
	s_waitcnt lgkmcnt(10)
	v_mfma_f32_32x32x16_bf16 v[82:97], v[186:189], v[138:141], v[82:97]
	s_waitcnt lgkmcnt(9)
	v_mfma_f32_32x32x16_bf16 v[82:97], v[190:193], v[134:137], v[82:97]
	s_waitcnt lgkmcnt(8)
	v_mfma_f32_32x32x16_bf16 v[82:97], v[194:197], v[130:133], v[82:97]
	s_waitcnt lgkmcnt(7)
	v_mfma_f32_32x32x16_bf16 v[82:97], v[208:211], v[126:129], v[82:97]
	s_waitcnt lgkmcnt(6)
	v_mfma_f32_32x32x16_bf16 v[82:97], v[212:215], v[122:125], v[82:97]
	s_waitcnt lgkmcnt(5)
	v_mfma_f32_32x32x16_bf16 v[82:97], v[216:219], v[118:121], v[82:97]
	s_waitcnt lgkmcnt(4)
	v_mfma_f32_32x32x16_bf16 v[82:97], v[220:223], v[114:117], v[82:97]
	s_waitcnt lgkmcnt(3)
	v_mfma_f32_32x32x16_bf16 v[82:97], v[224:227], v[110:113], v[82:97]
	s_waitcnt lgkmcnt(2)
	v_mfma_f32_32x32x16_bf16 v[82:97], v[228:231], v[106:109], v[82:97]
	s_waitcnt lgkmcnt(1)
	v_mfma_f32_32x32x16_bf16 v[82:97], v[232:235], v[102:105], v[82:97]
	s_waitcnt lgkmcnt(0)
	v_mfma_f32_32x32x16_bf16 v[82:97], v[236:239], v[98:101], v[82:97]
	v_lshl_add_u64 v[162:163], v[162:163], 0, s[88:89]
	v_lshl_add_u64 v[158:159], v[158:159], 0, s[16:17]
	s_mul_i32 s101, s13, 0x4400
	v_add_u32_e32 v250, s101, v174
	v_add_u32_e32 v251, 0xc800, v250
	v_add_u32_e32 v252, 0xd800, v250
	v_add_u32_e32 v253, 0xe800, v250
	v_add_u32_e32 v250, 0xf800, v250
	ds_read2_b64 v[220:223], v251 offset1:2
	ds_read2_b64 v[224:227], v251 offset0:4 offset1:6
	ds_read2_b64 v[186:189], v252 offset0:32 offset1:34
	ds_read2_b64 v[190:193], v252 offset0:36 offset1:38
	ds_read2_b64 v[194:197], v253 offset0:64 offset1:66
	ds_read2_b64 v[208:211], v253 offset0:68 offset1:70
	ds_read2_b64 v[212:215], v250 offset0:96 offset1:98
	ds_read2_b64 v[216:219], v250 offset0:100 offset1:102
	s_nop 1
	v_max_f32_e32 v2, v83, v83
	v_max_f32_e32 v16, v82, v82
	v_max_f32_e32 v2, v16, v2
	v_max3_f32 v2, v2, v84, v85
	v_max3_f32 v2, v2, v86, v87
	v_max3_f32 v2, v2, v88, v89
	v_max3_f32 v2, v2, v90, v91
	v_max3_f32 v2, v2, v92, v93
	v_max3_f32 v2, v2, v94, v95
	v_max3_f32 v2, v2, v96, v97
	v_mul_f32_e32 v2, 0x3dd53b94, v2
	v_mov_b32_e32 v16, v2
	s_nop 1
	v_permlane32_swap_b32_e32 v2, v16
	v_max_f32_e32 v16, v16, v16
	v_max_f32_e32 v2, v2, v2
	v_max_f32_e32 v2, v2, v16
	v_sub_f32_e32 v16, v2, v173
	v_cmp_ge_f32_e32 vcc, s14, v16
	s_cmp_eq_u64 vcc, exec
	s_cbranch_scc1 .LBB0_957
	v_max_f32_e32 v2, v2, v2
	v_max_f32_e32 v16, v173, v173
	v_max_f32_e32 v16, v16, v2
	v_sub_f32_e32 v2, v173, v16
	v_exp_f32_e32 v2, v2
	v_mov_b32_e32 v173, v16
	v_pk_mul_f32 v[80:81], v[80:81], v[2:3] op_sel_hi:[1,0]
	v_pk_mul_f32 v[78:79], v[78:79], v[2:3] op_sel_hi:[1,0]
	v_pk_mul_f32 v[76:77], v[76:77], v[2:3] op_sel_hi:[1,0]
	v_pk_mul_f32 v[74:75], v[74:75], v[2:3] op_sel_hi:[1,0]
	v_pk_mul_f32 v[72:73], v[72:73], v[2:3] op_sel_hi:[1,0]
	v_pk_mul_f32 v[70:71], v[70:71], v[2:3] op_sel_hi:[1,0]
	v_pk_mul_f32 v[68:69], v[68:69], v[2:3] op_sel_hi:[1,0]
	v_pk_mul_f32 v[66:67], v[66:67], v[2:3] op_sel_hi:[1,0]
	v_pk_mul_f32 v[48:49], v[48:49], v[2:3] op_sel_hi:[1,0]
	v_pk_mul_f32 v[46:47], v[46:47], v[2:3] op_sel_hi:[1,0]
	v_pk_mul_f32 v[44:45], v[44:45], v[2:3] op_sel_hi:[1,0]
	v_pk_mul_f32 v[42:43], v[42:43], v[2:3] op_sel_hi:[1,0]
	v_pk_mul_f32 v[40:41], v[40:41], v[2:3] op_sel_hi:[1,0]
	v_pk_mul_f32 v[38:39], v[38:39], v[2:3] op_sel_hi:[1,0]
	v_pk_mul_f32 v[36:37], v[36:37], v[2:3] op_sel_hi:[1,0]
	v_pk_mul_f32 v[34:35], v[34:35], v[2:3] op_sel_hi:[1,0]
	v_pk_mul_f32 v[64:65], v[64:65], v[2:3] op_sel_hi:[1,0]
	v_pk_mul_f32 v[62:63], v[62:63], v[2:3] op_sel_hi:[1,0]
	v_pk_mul_f32 v[60:61], v[60:61], v[2:3] op_sel_hi:[1,0]
	v_pk_mul_f32 v[58:59], v[58:59], v[2:3] op_sel_hi:[1,0]
	v_pk_mul_f32 v[56:57], v[56:57], v[2:3] op_sel_hi:[1,0]
	v_pk_mul_f32 v[54:55], v[54:55], v[2:3] op_sel_hi:[1,0]
	v_pk_mul_f32 v[52:53], v[52:53], v[2:3] op_sel_hi:[1,0]
	v_pk_mul_f32 v[50:51], v[50:51], v[2:3] op_sel_hi:[1,0]
	v_pk_mul_f32 v[32:33], v[32:33], v[2:3] op_sel_hi:[1,0]
	v_pk_mul_f32 v[30:31], v[30:31], v[2:3] op_sel_hi:[1,0]
	v_pk_mul_f32 v[28:29], v[28:29], v[2:3] op_sel_hi:[1,0]
	v_pk_mul_f32 v[26:27], v[26:27], v[2:3] op_sel_hi:[1,0]
	v_pk_mul_f32 v[24:25], v[24:25], v[2:3] op_sel_hi:[1,0]
	v_pk_mul_f32 v[22:23], v[22:23], v[2:3] op_sel_hi:[1,0]
	v_pk_mul_f32 v[20:21], v[20:21], v[2:3] op_sel_hi:[1,0]
	v_pk_mul_f32 v[18:19], v[18:19], v[2:3] op_sel_hi:[1,0]
	v_mul_f32_e32 v171, v171, v2
	s_branch .LBB0_957

.Lmla_inact:
	s_or_b64 exec, exec, s[50:51]
	v_lshl_add_u64 v[162:163], v[162:163], 0, s[88:89]
	v_lshl_add_u64 v[158:159], v[158:159], 0, s[16:17]
	v_add_co_u32_e32 v246, vcc, 0xfff80000, v162
	v_lshl_add_u64 v[240:241], v[158:159], 0, v[164:165]
	v_lshl_add_u64 v[242:243], v[158:159], 0, v[168:169]
	v_lshl_add_u64 v[244:245], v[158:159], 0, v[166:167]
	v_addc_co_u32_e32 v247, vcc, -1, v163, vcc
	global_load_dwordx4 v[12:15], v[240:241], off
	global_load_dwordx4 v[4:7], v[242:243], off
	global_load_dwordx4 v[8:11], v[244:245], off
	global_load_dwordx4 v[150:153], v[246:247], off
	global_load_dwordx4 v[146:149], v[162:163], off
	s_branch .LBB0_958
